# grid barrier: non-leader groups spin on the top-level generation word; per-XCD generation word no longer written
# baseline (speedup 1.0000x reference)
; DI unsigned xb_ld(unsigned* p)              { return __hip_atomic_load(p, __ATOMIC_RELAXED, __HIP_MEMORY_SCOPE_AGENT); }
; DI unsigned xb_add(unsigned* p, unsigned v) { return __hip_atomic_fetch_add(p, v, __ATOMIC_RELAXED, __HIP_MEMORY_SCOPE_AGENT); }
; #define XB_SPIN(cond, bar) do { unsigned _sp = 0; while (cond) { __builtin_amdgcn_s_sleep(1); \
;     if ((++_sp & 255u) == 0u) { if (xb_ld(&(bar)[XB_TMO])) break; if (_sp > XB_SPIN_CAP) { atomicAdd(&(bar)[XB_TMO], 1u); break; } } } } while (0)
; DI void xcd_barrier(const XcdBarrier& b, const int gw) {
;     ...
;         const unsigned old = xb_add(&bar[XB_XSUB(b.x)], 1u);
;         const unsigned gen = old / nloc;
;         if (old + 1u == (gen + 1u) * nloc) {
;             __builtin_amdgcn_fence(__ATOMIC_RELEASE, "agent");
;             asm volatile("s_waitcnt vmcnt(0)" ::: "memory");
;             const unsigned og = xb_add(&bar[XB_TOP], 1u);
;             const unsigned tg = og / nx;
;             if (og + 1u == (tg + 1u) * nx) xb_add(&bar[XB_TOPGEN], 1u);
;             else XB_SPIN(xb_ld(&bar[XB_TOPGEN]) == tg, bar);
;             __builtin_amdgcn_fence(__ATOMIC_ACQUIRE, "agent");
;             xb_add(&bar[XB_XGEN(b.x)], 1u);
;             asm volatile("s_waitcnt vmcnt(0)" ::: "memory");
;         } else {
;             XB_SPIN(xb_ld(&bar[XB_XGEN(b.x)]) == gen, bar);
.LBB0_146:
	s_or_b64 exec, exec, s[10:11]
	v_cvt_f32_u32_e32 v4, v2
	s_waitcnt vmcnt(0)
	v_readfirstlane_b32 s8, v3
	v_sub_u32_e32 v3, 0, v2
	v_rcp_iflag_f32_e32 v4, v4
	v_add_u32_e32 v5, s8, v1
	v_mul_f32_e32 v4, 0x4f7ffffe, v4
	v_cvt_u32_f32_e32 v4, v4
	v_mul_lo_u32 v1, v3, v4
	v_mul_hi_u32 v1, v4, v1
	v_add_u32_e32 v1, v4, v1
	v_mul_hi_u32 v1, v5, v1
	v_mul_lo_u32 v3, v1, v2
	v_sub_u32_e32 v3, v5, v3
	v_add_u32_e32 v4, 1, v1
	v_cmp_ge_u32_e32 vcc, v3, v2
	s_nop 1
	v_cndmask_b32_e32 v1, v1, v4, vcc
	v_sub_u32_e32 v4, v3, v2
	v_cndmask_b32_e32 v3, v3, v4, vcc
	v_add_u32_e32 v4, 1, v1
	v_cmp_ge_u32_e32 vcc, v3, v2
	v_add_u32_e32 v3, 1, v5
	s_nop 0
	v_cndmask_b32_e32 v1, v1, v4, vcc
	v_mul_lo_u32 v4, v2, v1
	v_add_u32_e32 v2, v4, v2
	v_cmp_ne_u32_e32 vcc, v3, v2
	s_and_saveexec_b64 s[8:9], vcc
	s_xor_b64 s[8:9], exec, s[8:9]
	s_cbranch_execz .LBB0_160
	s_waitcnt lgkmcnt(0)
	v_readlane_b32 s12, v254, 52
	v_readlane_b32 s13, v254, 53
	s_nop 4
	global_load_dword v0, v33, s[12:13] sc1
	s_waitcnt vmcnt(0)
	v_cmp_eq_u32_e32 vcc, v0, v1
	s_and_saveexec_b64 s[10:11], vcc
	s_cbranch_execz .LBB0_159
	s_mov_b32 s24, 1
	s_mov_b64 s[14:15], 0
	s_branch .LBB0_150

; DI unsigned xb_add(unsigned* p, unsigned v) { return __hip_atomic_fetch_add(p, v, __ATOMIC_RELAXED, __HIP_MEMORY_SCOPE_AGENT); }
; DI void xcd_barrier(const XcdBarrier& b, const int gw) {
;     ...
;             __builtin_amdgcn_fence(__ATOMIC_ACQUIRE, "agent");
;             xb_add(&bar[XB_XGEN(b.x)], 1u);
;             asm volatile("s_waitcnt vmcnt(0)" ::: "memory");
.LBB0_177:
	s_or_b64 exec, exec, s[8:9]
	s_mov_b64 s[8:9], exec
	v_mbcnt_lo_u32_b32 v0, s8, 0
	v_mbcnt_hi_u32_b32 v0, s9, v0
	v_cmp_eq_u32_e32 vcc, 0, v0
	s_waitcnt vmcnt(0)
	buffer_inv sc1
	s_and_saveexec_b64 s[10:11], vcc
	s_cbranch_execz .LBB0_179
	s_bcnt1_i32_b64 s8, s[8:9]
	v_mov_b32_e32 v0, s8
	v_mov_b32_e32 v1, 0x2000
.LBB0_179:
	s_or_b64 exec, exec, s[10:11]
	s_waitcnt vmcnt(0)

; DI unsigned xb_add(unsigned* p, unsigned v) { return __hip_atomic_fetch_add(p, v, __ATOMIC_RELAXED, __HIP_MEMORY_SCOPE_AGENT); }
; DI void xcd_barrier(const XcdBarrier& b, const int gw) {
;     ...
;             __builtin_amdgcn_fence(__ATOMIC_ACQUIRE, "agent");
;             xb_add(&bar[XB_XGEN(b.x)], 1u);
;             asm volatile("s_waitcnt vmcnt(0)" ::: "memory");
.LBB0_545:
	s_or_b64 exec, exec, s[8:9]
	s_mov_b64 s[8:9], exec
	v_mbcnt_lo_u32_b32 v0, s8, 0
	v_mbcnt_hi_u32_b32 v0, s9, v0
	v_cmp_eq_u32_e32 vcc, 0, v0
	s_waitcnt vmcnt(0)
	buffer_inv sc1
	s_and_saveexec_b64 s[10:11], vcc
	s_cbranch_execz .LBB0_547
	s_bcnt1_i32_b64 s8, s[8:9]
	v_mov_b32_e32 v0, s8
	v_mov_b32_e32 v1, 0x2000
.LBB0_547:
	s_or_b64 exec, exec, s[10:11]
	s_waitcnt vmcnt(0)
